# prologue FF1 weight transpose: the 32 LayerNorm gamma/beta scalar pairs per item preloaded up front (counted waits) instead of 32 serialized load+vmcnt(0) round trips
# baseline (speedup 1.0000x reference)
; #define lane (pg8::pg8_lane_id())
;     const int nblk = N / 32, kb = item / nblk, nb = item % nblk, k0 = 64 * kb, n0 = 32 * nb;
;     float s1 = 0.f, s2 = 0.f; float wv[32];
; #pragma unroll
;     for (int i = 0; i < 32; ++i) wv[i] = __builtin_nontemporal_load(W + (size_t)(k0 + 2 * i + (lane >> 5)) * N + n0 + (lane & 31));
; #pragma unroll
;     for (int i = 0; i < 32; ++i) { const int kk = 2 * i + (lane >> 5); float w = wv[i];
;         if (gv) { const float gk = gv[k0 + kk], bk = bv[k0 + kk]; s2 += w * bk; w *= gk; s1 += w; }
.LBB0_19:
	s_andn2_b64 vcc, exec, s[4:5]
	s_cbranch_vccnz .LBB0_89
	s_load_dwordx2 s[22:23], s[12:13], 0xa0
	s_load_dwordx4 s[4:7], s[12:13], 0x80
	s_add_i32 s95, s94, 0xffffcc00
	s_lshr_b32 s20, s95, 13
	s_lshl_b64 s[24:25], s[20:21], 26
	s_waitcnt lgkmcnt(0)
	s_add_u32 s24, s22, s24
	s_mov_b32 s76, s96
	s_addc_u32 s25, s23, s25
	s_and_b32 s96, s95, 0xffffe000
	s_add_u32 s22, s4, s96
	s_addc_u32 s23, s5, 0
	s_add_u32 s6, s6, s96
	s_addc_u32 s7, s7, 0
	s_lshr_b32 s95, s95, 2
	s_and_b32 s96, s95, 0x7c0
	s_and_b32 s95, s31, 0x1fe0
	s_lshl_b32 s97, s95, 2
	v_add_u32_e32 v14, s96, v25
	s_add_u32 s24, s24, s97
	s_addc_u32 s25, s25, 0
	v_ashrrev_i32_e32 v15, 31, v14
	s_cmp_lg_u64 s[4:5], 0
	s_cbranch_scc0 .Lpro_ff1_nog
	v_lshlrev_b64 v[106:107], 2, v[14:15]
	v_lshl_add_u64 v[108:109], s[6:7], 0, v[106:107]
	v_lshl_add_u64 v[106:107], s[22:23], 0, v[106:107]
	global_load_dword v111, v[106:107], off
	global_load_dword v110, v[108:109], off
	global_load_dword v113, v[106:107], off offset:8
	global_load_dword v112, v[108:109], off offset:8
	global_load_dword v115, v[106:107], off offset:16
	global_load_dword v114, v[108:109], off offset:16
	global_load_dword v117, v[106:107], off offset:24
	global_load_dword v116, v[108:109], off offset:24
	global_load_dword v119, v[106:107], off offset:32
	global_load_dword v118, v[108:109], off offset:32
	global_load_dword v121, v[106:107], off offset:40
	global_load_dword v120, v[108:109], off offset:40
	global_load_dword v123, v[106:107], off offset:48
	global_load_dword v122, v[108:109], off offset:48
	global_load_dword v125, v[106:107], off offset:56
	global_load_dword v124, v[108:109], off offset:56
	global_load_dword v127, v[106:107], off offset:64
	global_load_dword v126, v[108:109], off offset:64
	global_load_dword v129, v[106:107], off offset:72
	global_load_dword v128, v[108:109], off offset:72
	global_load_dword v131, v[106:107], off offset:80
	global_load_dword v130, v[108:109], off offset:80
	global_load_dword v133, v[106:107], off offset:88
	global_load_dword v132, v[108:109], off offset:88
	global_load_dword v135, v[106:107], off offset:96
	global_load_dword v134, v[108:109], off offset:96
	global_load_dword v137, v[106:107], off offset:104
	global_load_dword v136, v[108:109], off offset:104
	global_load_dword v139, v[106:107], off offset:112
	global_load_dword v138, v[108:109], off offset:112
	global_load_dword v141, v[106:107], off offset:120
	global_load_dword v140, v[108:109], off offset:120
	global_load_dword v143, v[106:107], off offset:128
	global_load_dword v142, v[108:109], off offset:128
	global_load_dword v145, v[106:107], off offset:136
	global_load_dword v144, v[108:109], off offset:136
	global_load_dword v147, v[106:107], off offset:144
	global_load_dword v146, v[108:109], off offset:144
	global_load_dword v149, v[106:107], off offset:152
	global_load_dword v148, v[108:109], off offset:152
	global_load_dword v151, v[106:107], off offset:160
	global_load_dword v150, v[108:109], off offset:160
	global_load_dword v153, v[106:107], off offset:168
	global_load_dword v152, v[108:109], off offset:168
	global_load_dword v155, v[106:107], off offset:176
	global_load_dword v154, v[108:109], off offset:176
	global_load_dword v157, v[106:107], off offset:184
	global_load_dword v156, v[108:109], off offset:184
	global_load_dword v159, v[106:107], off offset:192
	global_load_dword v158, v[108:109], off offset:192
	global_load_dword v161, v[106:107], off offset:200
	global_load_dword v160, v[108:109], off offset:200
	global_load_dword v163, v[106:107], off offset:208
	global_load_dword v162, v[108:109], off offset:208
	global_load_dword v165, v[106:107], off offset:216
	global_load_dword v164, v[108:109], off offset:216
	global_load_dword v167, v[106:107], off offset:224
	global_load_dword v166, v[108:109], off offset:224
	global_load_dword v169, v[106:107], off offset:232
	global_load_dword v168, v[108:109], off offset:232
	global_load_dword v171, v[106:107], off offset:240
	global_load_dword v170, v[108:109], off offset:240
	global_load_dword v173, v[106:107], off offset:248
	global_load_dword v172, v[108:109], off offset:248
; #define lane (pg8::pg8_lane_id())
;     ...
;     for (int i = 0; i < 32; ++i) wv[i] = __builtin_nontemporal_load(W + (size_t)(k0 + 2 * i + (lane >> 5)) * N + n0 + (lane & 31));
; #pragma unroll
;     for (int i = 0; i < 32; ++i) { const int kk = 2 * i + (lane >> 5); float w = wv[i];
;         if (gv) { const float gk = gv[k0 + kk], bk = bv[k0 + kk]; s2 += w * bk; w *= gk; s1 += w; }
.Lpro_ff1_nog:
	v_lshl_add_u64 v[18:19], s[24:25], 0, v[2:3]
	v_lshlrev_b64 v[20:21], 15, v[14:15]
	v_lshl_add_u64 v[18:19], v[18:19], 0, v[20:21]
	v_add_co_u32_e32 v20, vcc, s41, v18
	s_mov_b32 s24, 0xf0000
	s_nop 0
	v_addc_co_u32_e32 v21, vcc, 0, v19, vcc
	v_add_co_u32_e32 v68, vcc, s45, v18
	s_cmp_lg_u64 s[4:5], 0
	s_nop 0
	v_addc_co_u32_e32 v69, vcc, 0, v19, vcc
	v_add_co_u32_e32 v70, vcc, s49, v18
	v_lshlrev_b64 v[14:15], 2, v[14:15]
	s_nop 0
	v_addc_co_u32_e32 v71, vcc, 0, v19, vcc
	v_add_co_u32_e32 v72, vcc, s53, v18
	s_nop 1
	v_addc_co_u32_e32 v73, vcc, 0, v19, vcc
	v_add_co_u32_e32 v92, vcc, s57, v18
	s_nop 1
	v_addc_co_u32_e32 v93, vcc, 0, v19, vcc
	v_add_co_u32_e32 v94, vcc, s61, v18
	s_nop 1
	v_addc_co_u32_e32 v95, vcc, 0, v19, vcc
	v_add_co_u32_e32 v96, vcc, s65, v18
	s_nop 1
	v_addc_co_u32_e32 v97, vcc, 0, v19, vcc
	global_load_dword v80, v[18:19], off nt
	global_load_dword v78, v[20:21], off nt
	global_load_dword v76, v[68:69], off nt
	global_load_dword v74, v[70:71], off nt
	s_nop 0
	global_load_dword v72, v[72:73], off nt
	s_nop 0
	global_load_dword v70, v[92:93], off nt
	global_load_dword v68, v[94:95], off nt
	global_load_dword v64, v[96:97], off nt
	v_add_co_u32_e32 v20, vcc, s69, v18
	s_nop 1
	v_addc_co_u32_e32 v21, vcc, 0, v19, vcc
	v_add_co_u32_e32 v92, vcc, s70, v18
	s_nop 1
	v_addc_co_u32_e32 v93, vcc, 0, v19, vcc
	v_add_co_u32_e32 v94, vcc, s71, v18
	s_nop 1
	v_addc_co_u32_e32 v95, vcc, 0, v19, vcc
	v_add_co_u32_e32 v96, vcc, s72, v18
	s_nop 1
	v_addc_co_u32_e32 v97, vcc, 0, v19, vcc
	v_add_co_u32_e32 v98, vcc, s73, v18
	s_nop 1
	v_addc_co_u32_e32 v99, vcc, 0, v19, vcc
	v_add_co_u32_e32 v100, vcc, s74, v18
	s_nop 1
	v_addc_co_u32_e32 v101, vcc, 0, v19, vcc
	v_add_co_u32_e32 v102, vcc, s75, v18
	s_nop 1
	v_addc_co_u32_e32 v103, vcc, 0, v19, vcc
	v_add_co_u32_e32 v104, vcc, s24, v18
	s_mov_b32 s24, 0x100000
	s_nop 0
	v_addc_co_u32_e32 v105, vcc, 0, v19, vcc
	global_load_dword v66, v[20:21], off nt
	global_load_dword v62, v[92:93], off nt
	global_load_dword v60, v[94:95], off nt
	global_load_dword v58, v[96:97], off nt
	global_load_dword v56, v[98:99], off nt
	global_load_dword v54, v[100:101], off nt
	global_load_dword v50, v[102:103], off nt
	global_load_dword v46, v[104:105], off nt
	v_add_co_u32_e32 v20, vcc, s24, v18
	s_mov_b32 s24, 0x110000
	s_nop 0
	v_addc_co_u32_e32 v21, vcc, 0, v19, vcc
	v_add_co_u32_e32 v92, vcc, s24, v18
	s_mov_b32 s24, 0x120000
	s_nop 0
	v_addc_co_u32_e32 v93, vcc, 0, v19, vcc
	v_add_co_u32_e32 v94, vcc, s24, v18
	s_mov_b32 s24, 0x130000
	s_nop 0
	v_addc_co_u32_e32 v95, vcc, 0, v19, vcc
	v_add_co_u32_e32 v96, vcc, s24, v18
	s_mov_b32 s24, 0x140000
	s_nop 0
	v_addc_co_u32_e32 v97, vcc, 0, v19, vcc
	v_add_co_u32_e32 v98, vcc, s24, v18
	s_mov_b32 s24, 0x150000
	s_nop 0
	v_addc_co_u32_e32 v99, vcc, 0, v19, vcc
	v_add_co_u32_e32 v100, vcc, s24, v18
	s_mov_b32 s24, 0x160000
	s_nop 0
	v_addc_co_u32_e32 v101, vcc, 0, v19, vcc
	v_add_co_u32_e32 v102, vcc, s24, v18
	s_mov_b32 s24, 0x170000
	s_nop 0
	v_addc_co_u32_e32 v103, vcc, 0, v19, vcc
	v_add_co_u32_e32 v104, vcc, s24, v18
	s_cselect_b64 s[24:25], -1, 0
	s_nop 0
	v_addc_co_u32_e32 v105, vcc, 0, v19, vcc
	global_load_dword v52, v[20:21], off nt
	global_load_dword v48, v[92:93], off nt
	global_load_dword v44, v[94:95], off nt
	global_load_dword v42, v[96:97], off nt
	global_load_dword v40, v[98:99], off nt
	global_load_dword v38, v[100:101], off nt
	global_load_dword v34, v[102:103], off nt
	global_load_dword v30, v[104:105], off nt
	v_add_co_u32_e32 v20, vcc, s77, v18
	s_cmp_eq_u64 s[4:5], 0
	s_nop 0
	v_addc_co_u32_e32 v21, vcc, 0, v19, vcc
	v_add_co_u32_e32 v92, vcc, s78, v18
	s_nop 1
	v_addc_co_u32_e32 v93, vcc, 0, v19, vcc
	v_add_co_u32_e32 v94, vcc, s79, v18
	s_nop 1
	v_addc_co_u32_e32 v95, vcc, 0, v19, vcc
	v_add_co_u32_e32 v96, vcc, s80, v18
	s_nop 1
	v_addc_co_u32_e32 v97, vcc, 0, v19, vcc
	v_add_co_u32_e32 v98, vcc, s81, v18
	s_nop 1
	v_addc_co_u32_e32 v99, vcc, 0, v19, vcc
	v_add_co_u32_e32 v100, vcc, s84, v18
	s_nop 1
	v_addc_co_u32_e32 v101, vcc, 0, v19, vcc
	v_add_co_u32_e32 v102, vcc, 0x1e0000, v18
	s_nop 1
	v_addc_co_u32_e32 v103, vcc, 0, v19, vcc
	v_add_co_u32_e32 v18, vcc, 0x1f0000, v18
	s_nop 1
	v_addc_co_u32_e32 v19, vcc, 0, v19, vcc
	global_load_dword v36, v[20:21], off nt
	global_load_dword v32, v[92:93], off nt
	global_load_dword v28, v[94:95], off nt
	global_load_dword v26, v[96:97], off nt
	global_load_dword v24, v[98:99], off nt
	global_load_dword v22, v[100:101], off nt
	global_load_dword v16, v[102:103], off nt
	global_load_dword v13, v[18:19], off nt
	v_lshl_add_u64 v[18:19], s[22:23], 0, v[14:15]
	v_lshl_add_u64 v[20:21], s[6:7], 0, v[14:15]
	s_cbranch_scc1 .LBB0_22
	s_waitcnt vmcnt(31)
	v_pk_mul_f32 v[92:93], v[80:81], v[110:111] op_sel_hi:[0,1]
	v_pk_fma_f32 v[14:15], v[80:81], v[110:111], 0 op_sel_hi:[0,1,0]
	v_mov_b32_e32 v80, v93
	s_branch .LBB0_23

; #define lane (pg8::pg8_lane_id())
;     ...
;     for (int i = 0; i < 32; ++i) { const int kk = 2 * i + (lane >> 5); float w = wv[i];
;         if (gv) { const float gk = gv[k0 + kk], bk = bv[k0 + kk]; s2 += w * bk; w *= gk; s1 += w; }
;         scr[kk * 33 + (lane & 31)] = w; }
.LBB0_23:
	v_cndmask_b32_e64 v69, 0, 1, s[24:25]
	v_cmp_ne_u32_e64 s[4:5], 1, v69
	s_andn2_b64 vcc, exec, s[24:25]
	s_waitcnt vmcnt(31)
	ds_write_b32 v29, v80
	s_cbranch_vccnz .LBB0_25
	s_waitcnt vmcnt(30)
	v_pk_mul_f32 v[94:95], v[78:79], v[112:113] op_sel_hi:[0,1]
	v_pk_fma_f32 v[14:15], v[78:79], v[112:113], v[14:15] op_sel_hi:[0,1,1]
	v_mov_b32_e32 v78, v95
.LBB0_25:
	v_add_u32_e32 v69, v27, v41
	s_and_b64 vcc, exec, s[4:5]
	s_waitcnt vmcnt(30)
	ds_write_b32 v69, v78
	s_cbranch_vccnz .LBB0_27
	s_waitcnt vmcnt(29)
	v_pk_mul_f32 v[94:95], v[76:77], v[114:115] op_sel_hi:[0,1]
	v_pk_fma_f32 v[14:15], v[76:77], v[114:115], v[14:15] op_sel_hi:[0,1,1]
	v_mov_b32_e32 v76, v95
.LBB0_27:
	v_add_u32_e32 v69, v27, v43
	s_and_b64 vcc, exec, s[4:5]
	s_waitcnt vmcnt(29)
	ds_write_b32 v69, v76
	s_cbranch_vccnz .LBB0_29
	s_waitcnt vmcnt(28)
	v_pk_mul_f32 v[94:95], v[74:75], v[116:117] op_sel_hi:[0,1]
	v_pk_fma_f32 v[14:15], v[74:75], v[116:117], v[14:15] op_sel_hi:[0,1,1]
	v_mov_b32_e32 v74, v95
.LBB0_29:
	v_add_u32_e32 v69, v27, v45
	s_and_b64 vcc, exec, s[4:5]
	s_waitcnt vmcnt(28)
	ds_write_b32 v69, v74
	s_cbranch_vccnz .LBB0_31
	s_waitcnt vmcnt(27)
	v_pk_mul_f32 v[94:95], v[72:73], v[118:119] op_sel_hi:[0,1]
	v_pk_fma_f32 v[14:15], v[72:73], v[118:119], v[14:15] op_sel_hi:[0,1,1]
	v_mov_b32_e32 v72, v95
.LBB0_31:
	v_add_u32_e32 v69, v27, v47
	s_and_b64 vcc, exec, s[4:5]
	s_waitcnt vmcnt(27)
	ds_write_b32 v69, v72
	s_cbranch_vccnz .LBB0_33
	s_waitcnt vmcnt(26)
	v_pk_mul_f32 v[92:93], v[70:71], v[120:121] op_sel_hi:[0,1]
	v_pk_fma_f32 v[14:15], v[70:71], v[120:121], v[14:15] op_sel_hi:[0,1,1]
	v_mov_b32_e32 v70, v93
.LBB0_33:
	v_add_u32_e32 v69, v27, v49
	s_and_b64 vcc, exec, s[4:5]
	s_waitcnt vmcnt(26)
	ds_write_b32 v69, v70
	s_cbranch_vccnz .LBB0_35
	s_waitcnt vmcnt(25)
	v_pk_mul_f32 v[72:73], v[68:69], v[122:123] op_sel_hi:[0,1]
	v_pk_fma_f32 v[14:15], v[68:69], v[122:123], v[14:15] op_sel_hi:[0,1,1]
	v_mov_b32_e32 v68, v73
.LBB0_35:
	v_add_u32_e32 v69, v27, v51
	s_and_b64 vcc, exec, s[4:5]
	s_waitcnt vmcnt(25)
	ds_write_b32 v69, v68
	s_cbranch_vccnz .LBB0_37
	s_waitcnt vmcnt(24)
	v_pk_mul_f32 v[70:71], v[64:65], v[124:125] op_sel_hi:[0,1]
	v_pk_fma_f32 v[14:15], v[64:65], v[124:125], v[14:15] op_sel_hi:[0,1,1]
	v_mov_b32_e32 v64, v71
.LBB0_37:
	v_add_u32_e32 v68, v27, v53
	s_and_b64 vcc, exec, s[4:5]
	s_waitcnt vmcnt(24)
	ds_write_b32 v68, v64
	s_cbranch_vccnz .LBB0_39
	s_waitcnt vmcnt(23)
	v_pk_mul_f32 v[70:71], v[66:67], v[126:127] op_sel_hi:[0,1]
	v_pk_fma_f32 v[14:15], v[66:67], v[126:127], v[14:15] op_sel_hi:[0,1,1]
	v_mov_b32_e32 v66, v71
.LBB0_39:
	v_add_u32_e32 v64, v27, v55
	s_and_b64 vcc, exec, s[4:5]
	s_waitcnt vmcnt(23)
	ds_write_b32 v64, v66
	s_cbranch_vccnz .LBB0_41
	s_waitcnt vmcnt(22)
	v_pk_mul_f32 v[70:71], v[62:63], v[128:129] op_sel_hi:[0,1]
	v_pk_fma_f32 v[14:15], v[62:63], v[128:129], v[14:15] op_sel_hi:[0,1,1]
	v_mov_b32_e32 v62, v71
.LBB0_41:
	v_add_u32_e32 v64, v27, v57
	s_and_b64 vcc, exec, s[4:5]
	s_waitcnt vmcnt(22)
	ds_write_b32 v64, v62
	s_cbranch_vccnz .LBB0_43
	s_waitcnt vmcnt(21)
	v_pk_mul_f32 v[70:71], v[60:61], v[130:131] op_sel_hi:[0,1]
	v_pk_fma_f32 v[14:15], v[60:61], v[130:131], v[14:15] op_sel_hi:[0,1,1]
	v_mov_b32_e32 v60, v71
.LBB0_43:
	v_add_u32_e32 v62, v27, v59
	s_and_b64 vcc, exec, s[4:5]
	s_waitcnt vmcnt(21)
	ds_write_b32 v62, v60
	s_cbranch_vccnz .LBB0_45
	s_waitcnt vmcnt(20)
	v_pk_mul_f32 v[70:71], v[58:59], v[132:133] op_sel_hi:[0,1]
	v_pk_fma_f32 v[14:15], v[58:59], v[132:133], v[14:15] op_sel_hi:[0,1,1]
	v_mov_b32_e32 v58, v71
.LBB0_45:
	v_add_u32_e32 v60, v27, v61
	s_and_b64 vcc, exec, s[4:5]
	s_waitcnt vmcnt(20)
	ds_write_b32 v60, v58
	s_cbranch_vccnz .LBB0_47
	s_waitcnt vmcnt(19)
	v_pk_mul_f32 v[70:71], v[56:57], v[134:135] op_sel_hi:[0,1]
	v_pk_fma_f32 v[14:15], v[56:57], v[134:135], v[14:15] op_sel_hi:[0,1,1]
	v_mov_b32_e32 v56, v71
.LBB0_47:
	v_add_u32_e32 v58, v27, v63
	s_and_b64 vcc, exec, s[4:5]
	s_waitcnt vmcnt(19)
	ds_write_b32 v58, v56
	s_cbranch_vccnz .LBB0_49
	s_waitcnt vmcnt(18)
	v_pk_mul_f32 v[70:71], v[54:55], v[136:137] op_sel_hi:[0,1]
	v_pk_fma_f32 v[14:15], v[54:55], v[136:137], v[14:15] op_sel_hi:[0,1,1]
	v_mov_b32_e32 v54, v71
.LBB0_49:
	v_add_u32_e32 v56, v27, v65
	s_and_b64 vcc, exec, s[4:5]
	s_waitcnt vmcnt(18)
	ds_write_b32 v56, v54
	s_cbranch_vccnz .LBB0_51
	s_waitcnt vmcnt(17)
	v_pk_mul_f32 v[70:71], v[50:51], v[138:139] op_sel_hi:[0,1]
	v_pk_fma_f32 v[14:15], v[50:51], v[138:139], v[14:15] op_sel_hi:[0,1,1]
	v_mov_b32_e32 v50, v71
.LBB0_51:
	v_add_u32_e32 v54, v27, v67
	s_and_b64 vcc, exec, s[4:5]
	s_waitcnt vmcnt(17)
	ds_write_b32 v54, v50
	s_cbranch_vccnz .LBB0_53
	s_waitcnt vmcnt(16)
	v_pk_mul_f32 v[70:71], v[46:47], v[140:141] op_sel_hi:[0,1]
	v_pk_fma_f32 v[14:15], v[46:47], v[140:141], v[14:15] op_sel_hi:[0,1,1]
	v_mov_b32_e32 v46, v71
.LBB0_53:
	v_add_u32_e32 v50, v27, v75
	s_and_b64 vcc, exec, s[4:5]
	s_waitcnt vmcnt(16)
	ds_write_b32 v50, v46
	s_cbranch_vccnz .LBB0_55
	s_waitcnt vmcnt(15)
	v_pk_mul_f32 v[70:71], v[52:53], v[142:143] op_sel_hi:[0,1]
	v_pk_fma_f32 v[14:15], v[52:53], v[142:143], v[14:15] op_sel_hi:[0,1,1]
	v_mov_b32_e32 v52, v71
.LBB0_55:
	s_and_b64 vcc, exec, s[4:5]
	s_waitcnt vmcnt(15)
	ds_write_b32 v50, v52 offset:264
	s_cbranch_vccnz .LBB0_57
	s_waitcnt vmcnt(14)
	v_pk_mul_f32 v[70:71], v[48:49], v[144:145] op_sel_hi:[0,1]
	v_pk_fma_f32 v[14:15], v[48:49], v[144:145], v[14:15] op_sel_hi:[0,1,1]
	v_mov_b32_e32 v48, v71
.LBB0_57:
	s_and_b64 vcc, exec, s[4:5]
	s_waitcnt vmcnt(14)
	ds_write_b32 v50, v48 offset:528
	s_cbranch_vccnz .LBB0_59
	s_waitcnt vmcnt(13)
	v_pk_mul_f32 v[70:71], v[44:45], v[146:147] op_sel_hi:[0,1]
	v_pk_fma_f32 v[14:15], v[44:45], v[146:147], v[14:15] op_sel_hi:[0,1,1]
	v_mov_b32_e32 v44, v71
; __device__ __forceinline__ int p0_destcol(int col, int mode) { if (mode == 1) { const int x = col & 63; col = (col & ~63) + 32 * ((x >> 4) & 1) + 16 * (x >> 5) + (x & 15); } return col; }
; #define lane (pg8::pg8_lane_id())
;     ...
;     for (int i = 0; i < 32; ++i) { const int kk = 2 * i + (lane >> 5); float w = wv[i];
;         if (gv) { const float gk = gv[k0 + kk], bk = bv[k0 + kk]; s2 += w * bk; w *= gk; s1 += w; }
;         scr[kk * 33 + (lane & 31)] = w; }
;     if (gv) { s1 += __shfl_xor(s1, 32); s2 += __shfl_xor(s2, 32);
;         if (lane < 32) { const int dc = row_off + p0_destcol(n0 + lane, mode); atomicAdd(cs + dc, (unsigned long long)(long long)(s1 * 4294967296.0f)); atomicAdd(cs + CN + dc, (unsigned long long)(long long)(s2 * 4294967296.0f)); } }
.LBB0_59:
	s_and_b64 vcc, exec, s[4:5]
	s_waitcnt vmcnt(13)
	ds_write_b32 v50, v44 offset:792
	s_cbranch_vccnz .LBB0_61
	s_waitcnt vmcnt(12)
	v_pk_mul_f32 v[70:71], v[42:43], v[148:149] op_sel_hi:[0,1]
	v_pk_fma_f32 v[14:15], v[42:43], v[148:149], v[14:15] op_sel_hi:[0,1,1]
	v_mov_b32_e32 v42, v71
.LBB0_61:
	s_and_b64 vcc, exec, s[4:5]
	s_waitcnt vmcnt(12)
	ds_write_b32 v50, v42 offset:1056
	s_cbranch_vccnz .LBB0_63
	s_waitcnt vmcnt(11)
	v_pk_mul_f32 v[70:71], v[40:41], v[150:151] op_sel_hi:[0,1]
	v_pk_fma_f32 v[14:15], v[40:41], v[150:151], v[14:15] op_sel_hi:[0,1,1]
	v_mov_b32_e32 v40, v71
.LBB0_63:
	s_and_b64 vcc, exec, s[4:5]
	s_waitcnt vmcnt(11)
	ds_write_b32 v50, v40 offset:1320
	s_cbranch_vccnz .LBB0_65
	s_waitcnt vmcnt(10)
	v_pk_mul_f32 v[70:71], v[38:39], v[152:153] op_sel_hi:[0,1]
	v_pk_fma_f32 v[14:15], v[38:39], v[152:153], v[14:15] op_sel_hi:[0,1,1]
	v_mov_b32_e32 v38, v71
.LBB0_65:
	s_and_b64 vcc, exec, s[4:5]
	s_waitcnt vmcnt(10)
	ds_write_b32 v50, v38 offset:1584
	s_cbranch_vccnz .LBB0_67
	s_waitcnt vmcnt(9)
	v_pk_mul_f32 v[70:71], v[34:35], v[154:155] op_sel_hi:[0,1]
	v_pk_fma_f32 v[14:15], v[34:35], v[154:155], v[14:15] op_sel_hi:[0,1,1]
	v_mov_b32_e32 v34, v71
.LBB0_67:
	s_and_b64 vcc, exec, s[4:5]
	s_waitcnt vmcnt(9)
	ds_write_b32 v50, v34 offset:1848
	s_cbranch_vccnz .LBB0_69
	s_waitcnt vmcnt(8)
	v_pk_mul_f32 v[70:71], v[30:31], v[156:157] op_sel_hi:[0,1]
	v_pk_fma_f32 v[14:15], v[30:31], v[156:157], v[14:15] op_sel_hi:[0,1,1]
	v_mov_b32_e32 v30, v71
.LBB0_69:
	s_and_b64 vcc, exec, s[4:5]
	s_waitcnt vmcnt(8)
	ds_write_b32 v50, v30 offset:2112
	s_cbranch_vccnz .LBB0_71
	s_waitcnt vmcnt(7)
	v_pk_mul_f32 v[70:71], v[36:37], v[158:159] op_sel_hi:[0,1]
	v_pk_fma_f32 v[14:15], v[36:37], v[158:159], v[14:15] op_sel_hi:[0,1,1]
	v_mov_b32_e32 v36, v71
.LBB0_71:
	s_and_b64 vcc, exec, s[4:5]
	s_waitcnt vmcnt(7)
	ds_write_b32 v50, v36 offset:2376
	s_cbranch_vccnz .LBB0_73
	s_waitcnt vmcnt(6)
	v_pk_mul_f32 v[70:71], v[32:33], v[160:161] op_sel_hi:[0,1]
	v_pk_fma_f32 v[14:15], v[32:33], v[160:161], v[14:15] op_sel_hi:[0,1,1]
	v_mov_b32_e32 v32, v71
.LBB0_73:
	s_and_b64 vcc, exec, s[4:5]
	s_waitcnt vmcnt(6)
	ds_write_b32 v50, v32 offset:2640
	s_cbranch_vccnz .LBB0_75
	s_waitcnt vmcnt(5)
	v_pk_mul_f32 v[70:71], v[28:29], v[162:163] op_sel_hi:[0,1]
	v_pk_fma_f32 v[14:15], v[28:29], v[162:163], v[14:15] op_sel_hi:[0,1,1]
	v_mov_b32_e32 v28, v71
.LBB0_75:
	s_and_b64 vcc, exec, s[4:5]
	s_waitcnt vmcnt(5)
	ds_write_b32 v50, v28 offset:2904
	s_cbranch_vccnz .LBB0_77
	s_waitcnt vmcnt(4)
	v_pk_mul_f32 v[70:71], v[26:27], v[164:165] op_sel_hi:[0,1]
	v_pk_fma_f32 v[14:15], v[26:27], v[164:165], v[14:15] op_sel_hi:[0,1,1]
	v_mov_b32_e32 v26, v71
.LBB0_77:
	s_and_b64 vcc, exec, s[4:5]
	s_waitcnt vmcnt(4)
	ds_write_b32 v50, v26 offset:3168
	s_cbranch_vccnz .LBB0_79
	s_waitcnt vmcnt(3)
	v_pk_mul_f32 v[70:71], v[24:25], v[166:167] op_sel_hi:[0,1]
	v_pk_fma_f32 v[14:15], v[24:25], v[166:167], v[14:15] op_sel_hi:[0,1,1]
	v_mov_b32_e32 v24, v71
.LBB0_79:
	s_and_b64 vcc, exec, s[4:5]
	s_waitcnt vmcnt(3)
	ds_write_b32 v50, v24 offset:3432
	s_cbranch_vccnz .LBB0_81
	s_waitcnt vmcnt(2)
	v_pk_mul_f32 v[70:71], v[22:23], v[168:169] op_sel_hi:[0,1]
	v_pk_fma_f32 v[14:15], v[22:23], v[168:169], v[14:15] op_sel_hi:[0,1,1]
	v_mov_b32_e32 v22, v71
.LBB0_81:
	s_and_b64 vcc, exec, s[4:5]
	s_waitcnt vmcnt(2)
	ds_write_b32 v50, v22 offset:3696
	s_cbranch_vccnz .LBB0_83
	s_waitcnt vmcnt(1)
	v_pk_mul_f32 v[70:71], v[16:17], v[170:171] op_sel_hi:[0,1]
	v_pk_fma_f32 v[14:15], v[16:17], v[170:171], v[14:15] op_sel_hi:[0,1,1]
	v_mov_b32_e32 v16, v71
.LBB0_83:
	s_and_b64 vcc, exec, s[4:5]
	s_waitcnt vmcnt(1)
	ds_write_b32 v50, v16 offset:3960
	s_cbranch_vccnz .LBB0_94
	v_mov_b32_e32 v16, v172
	s_nop 0
	v_mov_b32_e32 v19, v173
	v_and_b32_e32 v20, 64, v91
	v_xor_b32_e32 v18, 32, v91
	v_add_u32_e32 v20, 64, v20
	v_cmp_lt_i32_e32 vcc, v18, v20
	s_waitcnt vmcnt(0)
	v_fma_f32 v14, v13, v16, v14
	v_cndmask_b32_e32 v18, v91, v18, vcc
	v_lshlrev_b32_e32 v18, 2, v18
	s_waitcnt vmcnt(0)
	v_fmac_f32_e32 v15, v13, v19
	ds_bpermute_b32 v16, v18, v15
	ds_bpermute_b32 v18, v18, v14
	v_mul_f32_e32 v19, v13, v19
	ds_write_b32 v50, v19 offset:4224
	s_and_saveexec_b64 s[4:5], s[8:9]
	s_cbranch_execz .LBB0_86
	s_waitcnt lgkmcnt(2)
	v_add_f32_e32 v16, v15, v16
	v_mul_f32_e32 v16, 0x4f800000, v16
	v_trunc_f32_e32 v16, v16
	s_waitcnt lgkmcnt(1)
	v_add_f32_e32 v20, v14, v18
	v_mul_f32_e64 v18, |v16|, s85
	v_floor_f32_e32 v18, v18
	v_fma_f32 v19, v18, s87, |v16|
	v_cvt_u32_f32_e32 v18, v18
	v_cvt_u32_f32_e32 v19, v19
	v_ashrrev_i32_e32 v16, 31, v16
	s_lshl_b64 s[6:7], s[20:21], 17
	v_xor_b32_e32 v21, v18, v16
	v_xor_b32_e32 v18, v19, v16
	v_sub_co_u32_e32 v18, vcc, v18, v16
	s_add_u32 s6, s29, s6
	s_nop 0
	v_subb_co_u32_e32 v19, vcc, v21, v16, vcc
	v_mul_f32_e32 v16, 0x4f800000, v20
	v_trunc_f32_e32 v16, v16
	v_mul_f32_e64 v20, |v16|, s85
	v_floor_f32_e32 v20, v20
	v_fma_f32 v21, v20, s87, |v16|
	v_cvt_u32_f32_e32 v21, v21
	v_add_u32_e32 v14, s95, v17
	v_cvt_u32_f32_e32 v20, v20
	s_addc_u32 s7, s30, s7
	v_ashrrev_i32_e32 v15, 31, v14
	v_lshl_add_u64 v[14:15], v[14:15], 3, s[6:7]
	v_ashrrev_i32_e32 v16, 31, v16
	global_atomic_add_x2 v[14:15], v[18:19], off
	v_xor_b32_e32 v18, v21, v16
	v_xor_b32_e32 v19, v20, v16
	v_sub_co_u32_e32 v18, vcc, v18, v16
	s_nop 1
	v_subb_co_u32_e32 v19, vcc, v19, v16, vcc
	v_add_co_u32_e32 v14, vcc, 0x10000, v14
	s_nop 1
	v_addc_co_u32_e32 v15, vcc, 0, v15, vcc
	global_atomic_add_x2 v[14:15], v[18:19], off
